# grid barrier: XCD leader no longer bumps the per-XCD generation word (unused after the flat release)
# baseline (speedup 1.0000x reference)
; __device__ __forceinline__ unsigned xb_ld(unsigned* p)              { return __hip_atomic_load(p, __ATOMIC_RELAXED, __HIP_MEMORY_SCOPE_AGENT); }
; __device__ __forceinline__ unsigned xb_add(unsigned* p, unsigned v) { return __hip_atomic_fetch_add(p, v, __ATOMIC_RELAXED, __HIP_MEMORY_SCOPE_AGENT); }
; #define XB_SPIN(cond, bar) do { unsigned _sp = 0; while (cond) { __builtin_amdgcn_s_sleep(1); \
;     if ((++_sp & 255u) == 0u) { if (xb_ld(&(bar)[XB_TMO])) break; if (_sp > XB_SPIN_CAP) { atomicAdd(&(bar)[XB_TMO], 1u); break; } } } } while (0)
; __device__ __forceinline__ void xcd_barrier(const XcdBarrier& b) {
;     ...
;             if (og + 1u == (tg + 1u) * nx) xb_add(&bar[XB_TOPGEN], 1u);
;             else XB_SPIN(xb_ld(&bar[XB_TOPGEN]) == tg, bar);
;             __builtin_amdgcn_fence(__ATOMIC_ACQUIRE, "agent");
;             xb_add(&bar[XB_XGEN(b.x)], 1u);
;             asm volatile("s_waitcnt vmcnt(0)" ::: "memory");
.LBB9_200:
	s_or_b64 exec, exec, s[10:11]
	v_readlane_b32 s4, v254, 47
	v_readlane_b32 s5, v254, 48
	s_waitcnt vmcnt(0)
	buffer_inv sc1
	s_nop 2
	s_nop 0
	s_waitcnt vmcnt(0)

; __device__ __forceinline__ unsigned xb_ld(unsigned* p)              { return __hip_atomic_load(p, __ATOMIC_RELAXED, __HIP_MEMORY_SCOPE_AGENT); }
; __device__ __forceinline__ unsigned xb_add(unsigned* p, unsigned v) { return __hip_atomic_fetch_add(p, v, __ATOMIC_RELAXED, __HIP_MEMORY_SCOPE_AGENT); }
; #define XB_SPIN(cond, bar) do { unsigned _sp = 0; while (cond) { __builtin_amdgcn_s_sleep(1); \
;     if ((++_sp & 255u) == 0u) { if (xb_ld(&(bar)[XB_TMO])) break; if (_sp > XB_SPIN_CAP) { atomicAdd(&(bar)[XB_TMO], 1u); break; } } } } while (0)
; __device__ __forceinline__ void xcd_barrier(const XcdBarrier& b) {
;     ...
;             if (og + 1u == (tg + 1u) * nx) xb_add(&bar[XB_TOPGEN], 1u);
;             else XB_SPIN(xb_ld(&bar[XB_TOPGEN]) == tg, bar);
;             __builtin_amdgcn_fence(__ATOMIC_ACQUIRE, "agent");
;             xb_add(&bar[XB_XGEN(b.x)], 1u);
;             asm volatile("s_waitcnt vmcnt(0)" ::: "memory");
.LBB9_1720:
	s_or_b64 exec, exec, s[14:15]
	v_readlane_b32 s4, v254, 47
	v_readlane_b32 s5, v254, 48
	s_waitcnt vmcnt(0)
	buffer_inv sc1
	s_nop 2
	s_nop 0
	s_waitcnt vmcnt(0)
